# hand-scheduled SwiGLU epilogue with packed f32 mul/add, batched exp/rcp
# speedup vs baseline: 1.0266x; 1.0059x over previous
; __device__ __forceinline__ unsigned cvt_pk_bf16(float lo, float hi) { unsigned r; asm volatile("v_cvt_pk_bf16_f32 %0, %1, %2" : "=v"(r) : "v"(lo), "v"(hi)); return r; }
; __device__ __forceinline__ float silu_mul(float g, float u) { return g * __builtin_amdgcn_rcpf(1.0f + __builtin_amdgcn_exp2f(-g * LOG2E)) * u; }
;     __device__ __forceinline__ void operator()(const f32x4 (&acc)[2][2][4][2], const Unit& u, int wr, int wc, int fr, int fq, int ui) const {
;         const int row0 = u.pm * 256 + wr * 64 + fr, hc = u.pn * 128 + wc * 32 + 8 * fq;
; #pragma unroll
;         for (int ai = 0; ai < 2; ++ai)
; #pragma unroll
;             for (int m = 0; m < 4; ++m) {
;                 const int r = row0 + ai * 128 + m * 16; const float rs = rsl[ui * 256 + wr * 64 + fr + ai * 128 + m * 16];
;                 const f32x4 g0 = acc[ai][0][m][0] * rs, g1 = acc[ai][0][m][1] * rs, u0 = acc[ai][1][m][0] * rs, u1 = acc[ai][1][m][1] * rs;
;                 u32x4 w;
;                 w.x = cvt_pk_bf16(silu_mul(g0[0], u0[0]), silu_mul(g0[1], u0[1])); w.y = cvt_pk_bf16(silu_mul(g0[2], u0[2]), silu_mul(g0[3], u0[3]));
;                 w.z = cvt_pk_bf16(silu_mul(g1[0], u1[0]), silu_mul(g1[1], u1[1])); w.w = cvt_pk_bf16(silu_mul(g1[2], u1[2]), silu_mul(g1[3], u1[3]));
;                 *(u32x4*)(H + (size_t)r * DFF + hc) = w;
;             }
.LBB0_218:
	v_lshl_add_u32 v147, s18, 10, v144
	v_lshl_or_b32 v140, s19, 7, v145
	v_lshl_add_u32 v148, s20, 8, v142
	v_ashrrev_i32_e32 v141, 31, v140
	s_mov_b64 s[54:55], -1
	s_andn2_b64 vcc, exec, s[44:45]
	ds_read_b32 v162, v147
	ds_read_b32 v164, v147 offset:64
	ds_read_b32 v166, v147 offset:128
	ds_read_b32 v168, v147 offset:192
	ds_read_b32 v170, v147 offset:512
	ds_read_b32 v172, v147 offset:576
	ds_read_b32 v174, v147 offset:640
	ds_read_b32 v176, v147 offset:704
	v_mov_b32_e32 v150, 0xbfb8aa3b
	v_mov_b64_e32 v[178:179], s[30:31]
	v_lshlrev_b64 v[180:181], 1, v[140:141]
	s_waitcnt lgkmcnt(7)
	v_pk_mul_f32 v[126:127], v[126:127], v[162:163] op_sel_hi:[1,0]
	v_pk_mul_f32 v[128:129], v[128:129], v[162:163] op_sel_hi:[1,0]
	v_pk_mul_f32 v[122:123], v[122:123], v[162:163] op_sel_hi:[1,0]
	v_pk_mul_f32 v[124:125], v[124:125], v[162:163] op_sel_hi:[1,0]
	v_pk_mul_f32 v[118:119], v[118:119], v[162:163] op_sel_hi:[1,0]
	v_pk_mul_f32 v[120:121], v[120:121], v[162:163] op_sel_hi:[1,0]
	v_pk_mul_f32 v[114:115], v[114:115], v[162:163] op_sel_hi:[1,0]
	v_pk_mul_f32 v[116:117], v[116:117], v[162:163] op_sel_hi:[1,0]
	v_pk_mul_f32 v[152:153], v[126:127], v[150:151] op_sel_hi:[1,0]
	v_pk_mul_f32 v[154:155], v[128:129], v[150:151] op_sel_hi:[1,0]
	v_pk_mul_f32 v[156:157], v[122:123], v[150:151] op_sel_hi:[1,0]
	v_pk_mul_f32 v[158:159], v[124:125], v[150:151] op_sel_hi:[1,0]
	v_exp_f32_e32 v152, v152
	v_exp_f32_e32 v153, v153
	v_exp_f32_e32 v154, v154
	v_exp_f32_e32 v155, v155
	v_exp_f32_e32 v156, v156
	v_exp_f32_e32 v157, v157
	v_exp_f32_e32 v158, v158
	v_exp_f32_e32 v159, v159
	v_pk_add_f32 v[152:153], v[152:153], 1.0 op_sel_hi:[1,0]
	v_pk_add_f32 v[154:155], v[154:155], 1.0 op_sel_hi:[1,0]
	v_pk_add_f32 v[156:157], v[156:157], 1.0 op_sel_hi:[1,0]
	v_pk_add_f32 v[158:159], v[158:159], 1.0 op_sel_hi:[1,0]
	v_rcp_f32_e32 v152, v152
	v_rcp_f32_e32 v153, v153
	v_rcp_f32_e32 v154, v154
	v_rcp_f32_e32 v155, v155
	v_rcp_f32_e32 v156, v156
	v_rcp_f32_e32 v157, v157
	v_rcp_f32_e32 v158, v158
	v_rcp_f32_e32 v159, v159
	v_pk_mul_f32 v[152:153], v[126:127], v[152:153]
	v_pk_mul_f32 v[154:155], v[128:129], v[154:155]
	v_pk_mul_f32 v[156:157], v[122:123], v[156:157]
	v_pk_mul_f32 v[158:159], v[124:125], v[158:159]
	v_pk_mul_f32 v[152:153], v[118:119], v[152:153]
	v_pk_mul_f32 v[154:155], v[120:121], v[154:155]
	v_pk_mul_f32 v[156:157], v[114:115], v[156:157]
	v_pk_mul_f32 v[158:159], v[116:117], v[158:159]
	v_cvt_pk_bf16_f32 v182, v152, v153
	v_cvt_pk_bf16_f32 v183, v154, v155
	v_cvt_pk_bf16_f32 v184, v156, v157
	v_cvt_pk_bf16_f32 v185, v158, v159
	v_mad_i64_i32 v[190:191], s[4:5], v148, s67, v[178:179]
	v_lshl_add_u64 v[190:191], v[190:191], 0, v[180:181]
	global_store_dwordx4 v[190:191], v[182:185], off
	s_waitcnt lgkmcnt(6)
	v_pk_mul_f32 v[110:111], v[110:111], v[164:165] op_sel_hi:[1,0]
	v_pk_mul_f32 v[112:113], v[112:113], v[164:165] op_sel_hi:[1,0]
	v_pk_mul_f32 v[106:107], v[106:107], v[164:165] op_sel_hi:[1,0]
	v_pk_mul_f32 v[108:109], v[108:109], v[164:165] op_sel_hi:[1,0]
	v_pk_mul_f32 v[102:103], v[102:103], v[164:165] op_sel_hi:[1,0]
	v_pk_mul_f32 v[104:105], v[104:105], v[164:165] op_sel_hi:[1,0]
	v_pk_mul_f32 v[98:99], v[98:99], v[164:165] op_sel_hi:[1,0]
	v_pk_mul_f32 v[100:101], v[100:101], v[164:165] op_sel_hi:[1,0]
	v_pk_mul_f32 v[152:153], v[110:111], v[150:151] op_sel_hi:[1,0]
	v_pk_mul_f32 v[154:155], v[112:113], v[150:151] op_sel_hi:[1,0]
	v_pk_mul_f32 v[156:157], v[106:107], v[150:151] op_sel_hi:[1,0]
	v_pk_mul_f32 v[158:159], v[108:109], v[150:151] op_sel_hi:[1,0]
	v_exp_f32_e32 v152, v152
	v_exp_f32_e32 v153, v153
	v_exp_f32_e32 v154, v154
	v_exp_f32_e32 v155, v155
	v_exp_f32_e32 v156, v156
	v_exp_f32_e32 v157, v157
	v_exp_f32_e32 v158, v158
	v_exp_f32_e32 v159, v159
	v_pk_add_f32 v[152:153], v[152:153], 1.0 op_sel_hi:[1,0]
	v_pk_add_f32 v[154:155], v[154:155], 1.0 op_sel_hi:[1,0]
	v_pk_add_f32 v[156:157], v[156:157], 1.0 op_sel_hi:[1,0]
	v_pk_add_f32 v[158:159], v[158:159], 1.0 op_sel_hi:[1,0]
	v_rcp_f32_e32 v152, v152
	v_rcp_f32_e32 v153, v153
	v_rcp_f32_e32 v154, v154
	v_rcp_f32_e32 v155, v155
	v_rcp_f32_e32 v156, v156
	v_rcp_f32_e32 v157, v157
	v_rcp_f32_e32 v158, v158
	v_rcp_f32_e32 v159, v159
	v_pk_mul_f32 v[152:153], v[110:111], v[152:153]
	v_pk_mul_f32 v[154:155], v[112:113], v[154:155]
	v_pk_mul_f32 v[156:157], v[106:107], v[156:157]
	v_pk_mul_f32 v[158:159], v[108:109], v[158:159]
	v_pk_mul_f32 v[152:153], v[102:103], v[152:153]
	v_pk_mul_f32 v[154:155], v[104:105], v[154:155]
	v_pk_mul_f32 v[156:157], v[98:99], v[156:157]
	v_pk_mul_f32 v[158:159], v[100:101], v[158:159]
	v_cvt_pk_bf16_f32 v186, v152, v153
	v_cvt_pk_bf16_f32 v187, v154, v155
	v_cvt_pk_bf16_f32 v188, v156, v157
	v_cvt_pk_bf16_f32 v189, v158, v159
	v_or_b32_e32 v149, 16, v148
	v_mad_i64_i32 v[190:191], s[4:5], v149, s67, v[178:179]
	v_lshl_add_u64 v[190:191], v[190:191], 0, v[180:181]
	global_store_dwordx4 v[190:191], v[186:189], off
	s_waitcnt lgkmcnt(5)
; __device__ __forceinline__ unsigned cvt_pk_bf16(float lo, float hi) { unsigned r; asm volatile("v_cvt_pk_bf16_f32 %0, %1, %2" : "=v"(r) : "v"(lo), "v"(hi)); return r; }
; __device__ __forceinline__ float silu_mul(float g, float u) { return g * __builtin_amdgcn_rcpf(1.0f + __builtin_amdgcn_exp2f(-g * LOG2E)) * u; }
;     __device__ __forceinline__ void operator()(const f32x4 (&acc)[2][2][4][2], const Unit& u, int wr, int wc, int fr, int fq, int ui) const {
;         const int row0 = u.pm * 256 + wr * 64 + fr, hc = u.pn * 128 + wc * 32 + 8 * fq;
; #pragma unroll
;         for (int ai = 0; ai < 2; ++ai)
; #pragma unroll
;             for (int m = 0; m < 4; ++m) {
;                 const int r = row0 + ai * 128 + m * 16; const float rs = rsl[ui * 256 + wr * 64 + fr + ai * 128 + m * 16];
;                 const f32x4 g0 = acc[ai][0][m][0] * rs, g1 = acc[ai][0][m][1] * rs, u0 = acc[ai][1][m][0] * rs, u1 = acc[ai][1][m][1] * rs;
;                 u32x4 w;
;                 w.x = cvt_pk_bf16(silu_mul(g0[0], u0[0]), silu_mul(g0[1], u0[1])); w.y = cvt_pk_bf16(silu_mul(g0[2], u0[2]), silu_mul(g0[3], u0[3]));
;                 w.z = cvt_pk_bf16(silu_mul(g1[0], u1[0]), silu_mul(g1[1], u1[1])); w.w = cvt_pk_bf16(silu_mul(g1[2], u1[2]), silu_mul(g1[3], u1[3]));
;                 *(u32x4*)(H + (size_t)r * DFF + hc) = w;
;             }
	v_pk_mul_f32 v[94:95], v[94:95], v[166:167] op_sel_hi:[1,0]
	v_pk_mul_f32 v[96:97], v[96:97], v[166:167] op_sel_hi:[1,0]
	v_pk_mul_f32 v[90:91], v[90:91], v[166:167] op_sel_hi:[1,0]
	v_pk_mul_f32 v[92:93], v[92:93], v[166:167] op_sel_hi:[1,0]
	v_pk_mul_f32 v[86:87], v[86:87], v[166:167] op_sel_hi:[1,0]
	v_pk_mul_f32 v[88:89], v[88:89], v[166:167] op_sel_hi:[1,0]
	v_pk_mul_f32 v[82:83], v[82:83], v[166:167] op_sel_hi:[1,0]
	v_pk_mul_f32 v[84:85], v[84:85], v[166:167] op_sel_hi:[1,0]
	v_pk_mul_f32 v[152:153], v[94:95], v[150:151] op_sel_hi:[1,0]
	v_pk_mul_f32 v[154:155], v[96:97], v[150:151] op_sel_hi:[1,0]
	v_pk_mul_f32 v[156:157], v[90:91], v[150:151] op_sel_hi:[1,0]
	v_pk_mul_f32 v[158:159], v[92:93], v[150:151] op_sel_hi:[1,0]
	v_exp_f32_e32 v152, v152
	v_exp_f32_e32 v153, v153
	v_exp_f32_e32 v154, v154
	v_exp_f32_e32 v155, v155
	v_exp_f32_e32 v156, v156
	v_exp_f32_e32 v157, v157
	v_exp_f32_e32 v158, v158
	v_exp_f32_e32 v159, v159
	v_pk_add_f32 v[152:153], v[152:153], 1.0 op_sel_hi:[1,0]
	v_pk_add_f32 v[154:155], v[154:155], 1.0 op_sel_hi:[1,0]
	v_pk_add_f32 v[156:157], v[156:157], 1.0 op_sel_hi:[1,0]
	v_pk_add_f32 v[158:159], v[158:159], 1.0 op_sel_hi:[1,0]
	v_rcp_f32_e32 v152, v152
	v_rcp_f32_e32 v153, v153
	v_rcp_f32_e32 v154, v154
	v_rcp_f32_e32 v155, v155
	v_rcp_f32_e32 v156, v156
	v_rcp_f32_e32 v157, v157
	v_rcp_f32_e32 v158, v158
	v_rcp_f32_e32 v159, v159
	v_pk_mul_f32 v[152:153], v[94:95], v[152:153]
	v_pk_mul_f32 v[154:155], v[96:97], v[154:155]
	v_pk_mul_f32 v[156:157], v[90:91], v[156:157]
	v_pk_mul_f32 v[158:159], v[92:93], v[158:159]
	v_pk_mul_f32 v[152:153], v[86:87], v[152:153]
	v_pk_mul_f32 v[154:155], v[88:89], v[154:155]
	v_pk_mul_f32 v[156:157], v[82:83], v[156:157]
	v_pk_mul_f32 v[158:159], v[84:85], v[158:159]
	v_cvt_pk_bf16_f32 v182, v152, v153
	v_cvt_pk_bf16_f32 v183, v154, v155
	v_cvt_pk_bf16_f32 v184, v156, v157
	v_cvt_pk_bf16_f32 v185, v158, v159
	v_or_b32_e32 v149, 32, v148
	v_mad_i64_i32 v[190:191], s[4:5], v149, s67, v[178:179]
	v_lshl_add_u64 v[190:191], v[190:191], 0, v[180:181]
	global_store_dwordx4 v[190:191], v[182:185], off
	s_waitcnt lgkmcnt(4)
	v_pk_mul_f32 v[78:79], v[78:79], v[168:169] op_sel_hi:[1,0]
	v_pk_mul_f32 v[80:81], v[80:81], v[168:169] op_sel_hi:[1,0]
	v_pk_mul_f32 v[74:75], v[74:75], v[168:169] op_sel_hi:[1,0]
	v_pk_mul_f32 v[76:77], v[76:77], v[168:169] op_sel_hi:[1,0]
	v_pk_mul_f32 v[70:71], v[70:71], v[168:169] op_sel_hi:[1,0]
	v_pk_mul_f32 v[72:73], v[72:73], v[168:169] op_sel_hi:[1,0]
	v_pk_mul_f32 v[66:67], v[66:67], v[168:169] op_sel_hi:[1,0]
	v_pk_mul_f32 v[68:69], v[68:69], v[168:169] op_sel_hi:[1,0]
	v_pk_mul_f32 v[152:153], v[78:79], v[150:151] op_sel_hi:[1,0]
	v_pk_mul_f32 v[154:155], v[80:81], v[150:151] op_sel_hi:[1,0]
	v_pk_mul_f32 v[156:157], v[74:75], v[150:151] op_sel_hi:[1,0]
	v_pk_mul_f32 v[158:159], v[76:77], v[150:151] op_sel_hi:[1,0]
	v_exp_f32_e32 v152, v152
	v_exp_f32_e32 v153, v153
	v_exp_f32_e32 v154, v154
	v_exp_f32_e32 v155, v155
	v_exp_f32_e32 v156, v156
	v_exp_f32_e32 v157, v157
	v_exp_f32_e32 v158, v158
	v_exp_f32_e32 v159, v159
	v_pk_add_f32 v[152:153], v[152:153], 1.0 op_sel_hi:[1,0]
	v_pk_add_f32 v[154:155], v[154:155], 1.0 op_sel_hi:[1,0]
	v_pk_add_f32 v[156:157], v[156:157], 1.0 op_sel_hi:[1,0]
	v_pk_add_f32 v[158:159], v[158:159], 1.0 op_sel_hi:[1,0]
	v_rcp_f32_e32 v152, v152
	v_rcp_f32_e32 v153, v153
	v_rcp_f32_e32 v154, v154
	v_rcp_f32_e32 v155, v155
	v_rcp_f32_e32 v156, v156
	v_rcp_f32_e32 v157, v157
	v_rcp_f32_e32 v158, v158
	v_rcp_f32_e32 v159, v159
	v_pk_mul_f32 v[152:153], v[78:79], v[152:153]
	v_pk_mul_f32 v[154:155], v[80:81], v[154:155]
	v_pk_mul_f32 v[156:157], v[74:75], v[156:157]
	v_pk_mul_f32 v[158:159], v[76:77], v[158:159]
	v_pk_mul_f32 v[152:153], v[70:71], v[152:153]
	v_pk_mul_f32 v[154:155], v[72:73], v[154:155]
	v_pk_mul_f32 v[156:157], v[66:67], v[156:157]
	v_pk_mul_f32 v[158:159], v[68:69], v[158:159]
	v_cvt_pk_bf16_f32 v186, v152, v153
	v_cvt_pk_bf16_f32 v187, v154, v155
	v_cvt_pk_bf16_f32 v188, v156, v157
	v_cvt_pk_bf16_f32 v189, v158, v159
	v_or_b32_e32 v149, 48, v148
	v_mad_i64_i32 v[190:191], s[4:5], v149, s67, v[178:179]
	v_lshl_add_u64 v[190:191], v[190:191], 0, v[180:181]
	global_store_dwordx4 v[190:191], v[186:189], off
	s_waitcnt lgkmcnt(3)
	v_pk_mul_f32 v[62:63], v[62:63], v[170:171] op_sel_hi:[1,0]
	v_pk_mul_f32 v[64:65], v[64:65], v[170:171] op_sel_hi:[1,0]
	v_pk_mul_f32 v[58:59], v[58:59], v[170:171] op_sel_hi:[1,0]
	v_pk_mul_f32 v[60:61], v[60:61], v[170:171] op_sel_hi:[1,0]
	v_pk_mul_f32 v[54:55], v[54:55], v[170:171] op_sel_hi:[1,0]
	v_pk_mul_f32 v[56:57], v[56:57], v[170:171] op_sel_hi:[1,0]
	v_pk_mul_f32 v[50:51], v[50:51], v[170:171] op_sel_hi:[1,0]
	v_pk_mul_f32 v[52:53], v[52:53], v[170:171] op_sel_hi:[1,0]
	v_pk_mul_f32 v[152:153], v[62:63], v[150:151] op_sel_hi:[1,0]
	v_pk_mul_f32 v[154:155], v[64:65], v[150:151] op_sel_hi:[1,0]
	v_pk_mul_f32 v[156:157], v[58:59], v[150:151] op_sel_hi:[1,0]
	v_pk_mul_f32 v[158:159], v[60:61], v[150:151] op_sel_hi:[1,0]
	v_exp_f32_e32 v152, v152
	v_exp_f32_e32 v153, v153
	v_exp_f32_e32 v154, v154
	v_exp_f32_e32 v155, v155
	v_exp_f32_e32 v156, v156
	v_exp_f32_e32 v157, v157
	v_exp_f32_e32 v158, v158
	v_exp_f32_e32 v159, v159
	v_pk_add_f32 v[152:153], v[152:153], 1.0 op_sel_hi:[1,0]
	v_pk_add_f32 v[154:155], v[154:155], 1.0 op_sel_hi:[1,0]
	v_pk_add_f32 v[156:157], v[156:157], 1.0 op_sel_hi:[1,0]
	v_pk_add_f32 v[158:159], v[158:159], 1.0 op_sel_hi:[1,0]
	v_rcp_f32_e32 v152, v152
	v_rcp_f32_e32 v153, v153
	v_rcp_f32_e32 v154, v154
	v_rcp_f32_e32 v155, v155
	v_rcp_f32_e32 v156, v156
	v_rcp_f32_e32 v157, v157
	v_rcp_f32_e32 v158, v158
	v_rcp_f32_e32 v159, v159
	v_pk_mul_f32 v[152:153], v[62:63], v[152:153]
	v_pk_mul_f32 v[154:155], v[64:65], v[154:155]
	v_pk_mul_f32 v[156:157], v[58:59], v[156:157]
	v_pk_mul_f32 v[158:159], v[60:61], v[158:159]
	v_pk_mul_f32 v[152:153], v[54:55], v[152:153]
	v_pk_mul_f32 v[154:155], v[56:57], v[154:155]
	v_pk_mul_f32 v[156:157], v[50:51], v[156:157]
	v_pk_mul_f32 v[158:159], v[52:53], v[158:159]
	v_cvt_pk_bf16_f32 v182, v152, v153
	v_cvt_pk_bf16_f32 v183, v154, v155
	v_cvt_pk_bf16_f32 v184, v156, v157
	v_cvt_pk_bf16_f32 v185, v158, v159
	v_add_u32_e32 v149, 0x80, v148
	v_mad_i64_i32 v[190:191], s[4:5], v149, s67, v[178:179]
	v_lshl_add_u64 v[190:191], v[190:191], 0, v[180:181]
	global_store_dwordx4 v[190:191], v[182:185], off
	s_waitcnt lgkmcnt(2)
; __device__ __forceinline__ unsigned cvt_pk_bf16(float lo, float hi) { unsigned r; asm volatile("v_cvt_pk_bf16_f32 %0, %1, %2" : "=v"(r) : "v"(lo), "v"(hi)); return r; }
; #define PG8_BAR __builtin_amdgcn_s_barrier()
; __device__ __forceinline__ float silu_mul(float g, float u) { return g * __builtin_amdgcn_rcpf(1.0f + __builtin_amdgcn_exp2f(-g * LOG2E)) * u; }
; template <class Epi, class Sched, bool ALIGN_EPI = false>
; __device__ __forceinline__ void gemm_phase(PG8_LAS unsigned char* lds, const Gemm g, const Sched& S, const Epi& E) {
;     ...
;         if (!has_next) break;
; #pragma unroll
;         for (int a = 0; a < 2; ++a)
; #pragma unroll
;             for (int b = 0; b < 2; ++b)
; #pragma unroll
;                 for (int m = 0; m < 4; ++m)
; #pragma unroll
;                     for (int n = 0; n < 2; ++n) acc[a][b][m][n] = (f32x4){0.f, 0.f, 0.f, 0.f};
;         cur = nxt; cA = nA; cB = nB; ++ui;
;         if constexpr (ALIGN_EPI) { if (wr == 1) PG8_BAR; }
;     __device__ __forceinline__ void operator()(const f32x4 (&acc)[2][2][4][2], const Unit& u, int wr, int wc, int fr, int fq, int ui) const {
;         const int row0 = u.pm * 256 + wr * 64 + fr, hc = u.pn * 128 + wc * 32 + 8 * fq;
; #pragma unroll
;         for (int ai = 0; ai < 2; ++ai)
; #pragma unroll
;             for (int m = 0; m < 4; ++m) {
;                 const int r = row0 + ai * 128 + m * 16; const float rs = rsl[ui * 256 + wr * 64 + fr + ai * 128 + m * 16];
;                 const f32x4 g0 = acc[ai][0][m][0] * rs, g1 = acc[ai][0][m][1] * rs, u0 = acc[ai][1][m][0] * rs, u1 = acc[ai][1][m][1] * rs;
;                 u32x4 w;
;                 w.x = cvt_pk_bf16(silu_mul(g0[0], u0[0]), silu_mul(g0[1], u0[1])); w.y = cvt_pk_bf16(silu_mul(g0[2], u0[2]), silu_mul(g0[3], u0[3]));
;                 w.z = cvt_pk_bf16(silu_mul(g1[0], u1[0]), silu_mul(g1[1], u1[1])); w.w = cvt_pk_bf16(silu_mul(g1[2], u1[2]), silu_mul(g1[3], u1[3]));
;                 *(u32x4*)(H + (size_t)r * DFF + hc) = w;
;             }
	v_pk_mul_f32 v[46:47], v[46:47], v[172:173] op_sel_hi:[1,0]
	v_pk_mul_f32 v[48:49], v[48:49], v[172:173] op_sel_hi:[1,0]
	v_pk_mul_f32 v[42:43], v[42:43], v[172:173] op_sel_hi:[1,0]
	v_pk_mul_f32 v[44:45], v[44:45], v[172:173] op_sel_hi:[1,0]
	v_pk_mul_f32 v[38:39], v[38:39], v[172:173] op_sel_hi:[1,0]
	v_pk_mul_f32 v[40:41], v[40:41], v[172:173] op_sel_hi:[1,0]
	v_pk_mul_f32 v[34:35], v[34:35], v[172:173] op_sel_hi:[1,0]
	v_pk_mul_f32 v[36:37], v[36:37], v[172:173] op_sel_hi:[1,0]
	v_pk_mul_f32 v[152:153], v[46:47], v[150:151] op_sel_hi:[1,0]
	v_pk_mul_f32 v[154:155], v[48:49], v[150:151] op_sel_hi:[1,0]
	v_pk_mul_f32 v[156:157], v[42:43], v[150:151] op_sel_hi:[1,0]
	v_pk_mul_f32 v[158:159], v[44:45], v[150:151] op_sel_hi:[1,0]
	v_exp_f32_e32 v152, v152
	v_exp_f32_e32 v153, v153
	v_exp_f32_e32 v154, v154
	v_exp_f32_e32 v155, v155
	v_exp_f32_e32 v156, v156
	v_exp_f32_e32 v157, v157
	v_exp_f32_e32 v158, v158
	v_exp_f32_e32 v159, v159
	v_pk_add_f32 v[152:153], v[152:153], 1.0 op_sel_hi:[1,0]
	v_pk_add_f32 v[154:155], v[154:155], 1.0 op_sel_hi:[1,0]
	v_pk_add_f32 v[156:157], v[156:157], 1.0 op_sel_hi:[1,0]
	v_pk_add_f32 v[158:159], v[158:159], 1.0 op_sel_hi:[1,0]
	v_rcp_f32_e32 v152, v152
	v_rcp_f32_e32 v153, v153
	v_rcp_f32_e32 v154, v154
	v_rcp_f32_e32 v155, v155
	v_rcp_f32_e32 v156, v156
	v_rcp_f32_e32 v157, v157
	v_rcp_f32_e32 v158, v158
	v_rcp_f32_e32 v159, v159
	v_pk_mul_f32 v[152:153], v[46:47], v[152:153]
	v_pk_mul_f32 v[154:155], v[48:49], v[154:155]
	v_pk_mul_f32 v[156:157], v[42:43], v[156:157]
	v_pk_mul_f32 v[158:159], v[44:45], v[158:159]
	v_pk_mul_f32 v[152:153], v[38:39], v[152:153]
	v_pk_mul_f32 v[154:155], v[40:41], v[154:155]
	v_pk_mul_f32 v[156:157], v[34:35], v[156:157]
	v_pk_mul_f32 v[158:159], v[36:37], v[158:159]
	v_cvt_pk_bf16_f32 v186, v152, v153
	v_cvt_pk_bf16_f32 v187, v154, v155
	v_cvt_pk_bf16_f32 v188, v156, v157
	v_cvt_pk_bf16_f32 v189, v158, v159
	v_add_u32_e32 v149, 0x90, v148
	v_mad_i64_i32 v[190:191], s[4:5], v149, s67, v[178:179]
	v_lshl_add_u64 v[190:191], v[190:191], 0, v[180:181]
	global_store_dwordx4 v[190:191], v[186:189], off
	s_waitcnt lgkmcnt(1)
	v_pk_mul_f32 v[30:31], v[30:31], v[174:175] op_sel_hi:[1,0]
	v_pk_mul_f32 v[32:33], v[32:33], v[174:175] op_sel_hi:[1,0]
	v_pk_mul_f32 v[26:27], v[26:27], v[174:175] op_sel_hi:[1,0]
	v_pk_mul_f32 v[28:29], v[28:29], v[174:175] op_sel_hi:[1,0]
	v_pk_mul_f32 v[22:23], v[22:23], v[174:175] op_sel_hi:[1,0]
	v_pk_mul_f32 v[24:25], v[24:25], v[174:175] op_sel_hi:[1,0]
	v_pk_mul_f32 v[18:19], v[18:19], v[174:175] op_sel_hi:[1,0]
	v_pk_mul_f32 v[20:21], v[20:21], v[174:175] op_sel_hi:[1,0]
	v_pk_mul_f32 v[152:153], v[30:31], v[150:151] op_sel_hi:[1,0]
	v_pk_mul_f32 v[154:155], v[32:33], v[150:151] op_sel_hi:[1,0]
	v_pk_mul_f32 v[156:157], v[26:27], v[150:151] op_sel_hi:[1,0]
	v_pk_mul_f32 v[158:159], v[28:29], v[150:151] op_sel_hi:[1,0]
	v_exp_f32_e32 v152, v152
	v_exp_f32_e32 v153, v153
	v_exp_f32_e32 v154, v154
	v_exp_f32_e32 v155, v155
	v_exp_f32_e32 v156, v156
	v_exp_f32_e32 v157, v157
	v_exp_f32_e32 v158, v158
	v_exp_f32_e32 v159, v159
	v_pk_add_f32 v[152:153], v[152:153], 1.0 op_sel_hi:[1,0]
	v_pk_add_f32 v[154:155], v[154:155], 1.0 op_sel_hi:[1,0]
	v_pk_add_f32 v[156:157], v[156:157], 1.0 op_sel_hi:[1,0]
	v_pk_add_f32 v[158:159], v[158:159], 1.0 op_sel_hi:[1,0]
	v_rcp_f32_e32 v152, v152
	v_rcp_f32_e32 v153, v153
	v_rcp_f32_e32 v154, v154
	v_rcp_f32_e32 v155, v155
	v_rcp_f32_e32 v156, v156
	v_rcp_f32_e32 v157, v157
	v_rcp_f32_e32 v158, v158
	v_rcp_f32_e32 v159, v159
	v_pk_mul_f32 v[152:153], v[30:31], v[152:153]
	v_pk_mul_f32 v[154:155], v[32:33], v[154:155]
	v_pk_mul_f32 v[156:157], v[26:27], v[156:157]
	v_pk_mul_f32 v[158:159], v[28:29], v[158:159]
	v_pk_mul_f32 v[152:153], v[22:23], v[152:153]
	v_pk_mul_f32 v[154:155], v[24:25], v[154:155]
	v_pk_mul_f32 v[156:157], v[18:19], v[156:157]
	v_pk_mul_f32 v[158:159], v[20:21], v[158:159]
	v_cvt_pk_bf16_f32 v182, v152, v153
	v_cvt_pk_bf16_f32 v183, v154, v155
	v_cvt_pk_bf16_f32 v184, v156, v157
	v_cvt_pk_bf16_f32 v185, v158, v159
	v_add_u32_e32 v149, 0xa0, v148
	v_mad_i64_i32 v[190:191], s[4:5], v149, s67, v[178:179]
	v_lshl_add_u64 v[190:191], v[190:191], 0, v[180:181]
	global_store_dwordx4 v[190:191], v[182:185], off
	s_waitcnt lgkmcnt(0)
	v_pk_mul_f32 v[14:15], v[14:15], v[176:177] op_sel_hi:[1,0]
	v_pk_mul_f32 v[16:17], v[16:17], v[176:177] op_sel_hi:[1,0]
	v_pk_mul_f32 v[10:11], v[10:11], v[176:177] op_sel_hi:[1,0]
	v_pk_mul_f32 v[12:13], v[12:13], v[176:177] op_sel_hi:[1,0]
	v_pk_mul_f32 v[6:7], v[6:7], v[176:177] op_sel_hi:[1,0]
	v_pk_mul_f32 v[8:9], v[8:9], v[176:177] op_sel_hi:[1,0]
	v_pk_mul_f32 v[2:3], v[2:3], v[176:177] op_sel_hi:[1,0]
	v_pk_mul_f32 v[4:5], v[4:5], v[176:177] op_sel_hi:[1,0]
	v_pk_mul_f32 v[152:153], v[14:15], v[150:151] op_sel_hi:[1,0]
	v_pk_mul_f32 v[154:155], v[16:17], v[150:151] op_sel_hi:[1,0]
	v_pk_mul_f32 v[156:157], v[10:11], v[150:151] op_sel_hi:[1,0]
	v_pk_mul_f32 v[158:159], v[12:13], v[150:151] op_sel_hi:[1,0]
	v_exp_f32_e32 v152, v152
	v_exp_f32_e32 v153, v153
	v_exp_f32_e32 v154, v154
	v_exp_f32_e32 v155, v155
	v_exp_f32_e32 v156, v156
	v_exp_f32_e32 v157, v157
	v_exp_f32_e32 v158, v158
	v_exp_f32_e32 v159, v159
	v_pk_add_f32 v[152:153], v[152:153], 1.0 op_sel_hi:[1,0]
	v_pk_add_f32 v[154:155], v[154:155], 1.0 op_sel_hi:[1,0]
	v_pk_add_f32 v[156:157], v[156:157], 1.0 op_sel_hi:[1,0]
	v_pk_add_f32 v[158:159], v[158:159], 1.0 op_sel_hi:[1,0]
	v_rcp_f32_e32 v152, v152
	v_rcp_f32_e32 v153, v153
	v_rcp_f32_e32 v154, v154
	v_rcp_f32_e32 v155, v155
	v_rcp_f32_e32 v156, v156
	v_rcp_f32_e32 v157, v157
	v_rcp_f32_e32 v158, v158
	v_rcp_f32_e32 v159, v159
	v_pk_mul_f32 v[152:153], v[14:15], v[152:153]
	v_pk_mul_f32 v[154:155], v[16:17], v[154:155]
	v_pk_mul_f32 v[156:157], v[10:11], v[156:157]
	v_pk_mul_f32 v[158:159], v[12:13], v[158:159]
	v_pk_mul_f32 v[152:153], v[6:7], v[152:153]
	v_pk_mul_f32 v[154:155], v[8:9], v[154:155]
	v_pk_mul_f32 v[156:157], v[2:3], v[156:157]
	v_pk_mul_f32 v[158:159], v[4:5], v[158:159]
	v_cvt_pk_bf16_f32 v186, v152, v153
	v_cvt_pk_bf16_f32 v187, v154, v155
	v_cvt_pk_bf16_f32 v188, v156, v157
	v_cvt_pk_bf16_f32 v189, v158, v159
	v_add_u32_e32 v149, 0xb0, v148
	v_mad_i64_i32 v[190:191], s[4:5], v149, s67, v[178:179]
	v_lshl_add_u64 v[190:191], v[190:191], 0, v[180:181]
	global_store_dwordx4 v[190:191], v[186:189], off
	s_cbranch_vccnz .LBB0_211
	s_andn2_b64 vcc, exec, s[28:29]
	s_cbranch_vccnz .LBB0_210
	s_barrier
	s_branch .LBB0_210
